# diff loops: s_setprio 1 moved ahead of the exposed exp block (priority placement only)
# baseline (speedup 1.0000x reference)
; #define MFMA32(a, b, c) __builtin_amdgcn_mfma_f32_32x32x16_bf16((a), (b), (c), 0, 0, 0)
; #define VFRAG(ptr, off0, STR) ({ const s16x4 lo_ = vtr((ptr) + (off0)); const s16x4 hi_ = vtr((ptr) + (off0) + 8 * (STR)); (bf16x8){lo_[0], lo_[1], lo_[2], lo_[3], hi_[0], hi_[1], hi_[2], hi_[3]}; })
; __device__ __forceinline__ void diff_unit(const Frame& F, int b, int h, int qi, float lam, int dry) {
;     ...
;             float ps = 0.f;
; #pragma unroll
;             for (int r = 0; r < 16; ++r) { s0[r] = __builtin_amdgcn_exp2f(s0[r] * LOG2E - ms); ps += s0[r]; }
;             if (!meta) {
; #pragma unroll
;                 for (int r = 0; r < 16; ++r) { s1[r] = __builtin_amdgcn_exp2f(s1[r] * LOG2E - ms); ps += s1[r]; }
;             }
;             lsum += ps;
;             __builtin_amdgcn_s_setprio(1);
;             { const bf16x8 pf = pack_step(s0, 0);
;               O[0] = MFMA32(vpre0, pf, O[0]); O[1] = MFMA32(vpre1, pf, O[1]); O[2] = MFMA32(vpre2, pf, O[2]); O[3] = MFMA32(vpre3, pf, O[3]); }
;             if (!meta) {
;                 { const bf16x8 pf = pack_step(s0, 1);
;                   O[0] = MFMA32(vprf0, pf, O[0]); O[1] = MFMA32(vprf1, pf, O[1]);
; #pragma unroll
;                   for (int dt = 2; dt < 4; ++dt) { const bf16x8 vf = VFRAG(vb, 16 * DV_STR + 64 * dt, DV_STR); O[dt] = MFMA32(vf, pf, O[dt]); } }
; #pragma unroll
;                 for (int s2 = 0; s2 < 2; ++s2) { const bf16x8 pf = pack_step(s1, s2);
; #pragma unroll
;                     for (int dt = 0; dt < 4; ++dt) { const bf16x8 vf = VFRAG(vb, (32 + 16 * s2) * DV_STR + 64 * dt, DV_STR); O[dt] = MFMA32(vf, pf, O[dt]); } }
;             }
;             __builtin_amdgcn_s_setprio(0);
.LBB0_305:
	s_setprio 1
	v_exp_f32_e32 v80, v80
	v_exp_f32_e32 v81, v81
	v_exp_f32_e32 v82, v82
	v_exp_f32_e32 v83, v83
	v_exp_f32_e32 v84, v84
	v_exp_f32_e32 v85, v85
	v_exp_f32_e32 v86, v86
	v_exp_f32_e32 v87, v87
	v_add_f32_e32 v236, v80, v82
	v_add_f32_e32 v237, v81, v83
	v_cvt_pk_bf16_f32 v232, v80, v81
	v_cvt_pk_bf16_f32 v233, v82, v83
	v_cvt_pk_bf16_f32 v234, v84, v85
	v_cvt_pk_bf16_f32 v235, v86, v87
	v_add_f32_e32 v236, v236, v84
	v_add_f32_e32 v237, v237, v85
	v_add_f32_e32 v236, v236, v86
	v_add_f32_e32 v237, v237, v87
	v_mfma_f32_32x32x16_bf16 v[48:63], v[148:151], v[232:235], v[48:63]
	ds_read_b64_tr_b16 v[148:149], v222 offset:45056
	ds_read_b64_tr_b16 v[150:151], v222 offset:47616
	v_exp_f32_e32 v88, v88
	v_exp_f32_e32 v89, v89
	v_mfma_f32_32x32x16_bf16 v[32:47], v[144:147], v[232:235], v[32:47]
	ds_read_b64_tr_b16 v[144:145], v222 offset:45120
	ds_read_b64_tr_b16 v[146:147], v222 offset:47680
	v_exp_f32_e32 v90, v90
	v_exp_f32_e32 v91, v91
	v_add_f32_e32 v236, v236, v88
	v_add_f32_e32 v237, v237, v89
	v_cvt_pk_bf16_f32 v80, v88, v89
	v_mfma_f32_32x32x16_bf16 v[16:31], v[140:143], v[232:235], v[16:31]
	ds_read_b64_tr_b16 v[140:141], v222 offset:45184
	ds_read_b64_tr_b16 v[142:143], v222 offset:47744
	v_exp_f32_e32 v92, v92
	v_exp_f32_e32 v93, v93
	v_add_f32_e32 v236, v236, v90
	v_add_f32_e32 v237, v237, v91
	v_cvt_pk_bf16_f32 v81, v90, v91
	v_mfma_f32_32x32x16_bf16 v[0:15], v[136:139], v[232:235], v[0:15]
	ds_read_b64_tr_b16 v[136:137], v222 offset:45248
	ds_read_b64_tr_b16 v[138:139], v222 offset:47808
	v_exp_f32_e32 v94, v94
	v_exp_f32_e32 v95, v95
	v_add_f32_e32 v236, v236, v92
	v_add_f32_e32 v237, v237, v93
	v_cvt_pk_bf16_f32 v82, v92, v93
	v_cvt_pk_bf16_f32 v83, v94, v95
	v_add_f32_e32 v236, v236, v94
	v_add_f32_e32 v237, v237, v95
	v_mfma_f32_32x32x16_bf16 v[48:63], v[128:131], v[80:83], v[48:63]
	ds_read_b64_tr_b16 v[128:129], v222 offset:50176
	ds_read_b64_tr_b16 v[130:131], v222 offset:52736
	v_exp_f32_e32 v64, v64
	v_exp_f32_e32 v65, v65
	v_mfma_f32_32x32x16_bf16 v[32:47], v[132:135], v[80:83], v[32:47]
	ds_read_b64_tr_b16 v[132:133], v222 offset:50240
	ds_read_b64_tr_b16 v[134:135], v222 offset:52800
	v_exp_f32_e32 v66, v66
	v_exp_f32_e32 v67, v67
	v_add_f32_e32 v236, v236, v64
	v_add_f32_e32 v237, v237, v65
	v_cvt_pk_bf16_f32 v84, v64, v65
	s_waitcnt lgkmcnt(14)
	v_mfma_f32_32x32x16_bf16 v[16:31], v[224:227], v[80:83], v[16:31]
	ds_read_b64_tr_b16 v[224:225], v222 offset:50304
	ds_read_b64_tr_b16 v[226:227], v222 offset:52864
	v_exp_f32_e32 v68, v68
	v_exp_f32_e32 v69, v69
	v_add_f32_e32 v236, v236, v66
	v_add_f32_e32 v237, v237, v67
	v_cvt_pk_bf16_f32 v85, v66, v67
	s_waitcnt lgkmcnt(14)
	v_mfma_f32_32x32x16_bf16 v[0:15], v[228:231], v[80:83], v[0:15]
	ds_read_b64_tr_b16 v[228:229], v222 offset:50368
	ds_read_b64_tr_b16 v[230:231], v222 offset:52928
	v_exp_f32_e32 v70, v70
	v_exp_f32_e32 v71, v71
	v_add_f32_e32 v236, v236, v68
	v_add_f32_e32 v237, v237, v69
	v_cvt_pk_bf16_f32 v86, v68, v69
	v_cvt_pk_bf16_f32 v87, v70, v71
	v_add_f32_e32 v236, v236, v70
	v_add_f32_e32 v237, v237, v71
	s_waitcnt lgkmcnt(8)
	v_mfma_f32_32x32x16_bf16 v[48:63], v[148:151], v[84:87], v[48:63]
	v_exp_f32_e32 v72, v72
	v_exp_f32_e32 v73, v73
	v_mfma_f32_32x32x16_bf16 v[32:47], v[144:147], v[84:87], v[32:47]
	v_exp_f32_e32 v74, v74
	v_exp_f32_e32 v75, v75
	v_add_f32_e32 v236, v236, v72
	v_add_f32_e32 v237, v237, v73
	v_cvt_pk_bf16_f32 v232, v72, v73
	v_mfma_f32_32x32x16_bf16 v[16:31], v[140:143], v[84:87], v[16:31]
	v_exp_f32_e32 v76, v76
	v_exp_f32_e32 v77, v77
	v_add_f32_e32 v236, v236, v74
	v_add_f32_e32 v237, v237, v75
	v_cvt_pk_bf16_f32 v233, v74, v75
	v_mfma_f32_32x32x16_bf16 v[0:15], v[136:139], v[84:87], v[0:15]
	v_exp_f32_e32 v78, v78
	v_exp_f32_e32 v79, v79
	v_add_f32_e32 v236, v236, v76
	v_add_f32_e32 v237, v237, v77
	v_cvt_pk_bf16_f32 v234, v76, v77
	v_cvt_pk_bf16_f32 v235, v78, v79
	v_add_f32_e32 v236, v236, v78
	v_add_f32_e32 v237, v237, v79
	v_add_f32_e32 v223, v236, v237
	v_add_f32_e32 v158, v158, v223
	s_waitcnt lgkmcnt(0)
	v_mfma_f32_32x32x16_bf16 v[48:63], v[128:131], v[232:235], v[48:63]
	v_mfma_f32_32x32x16_bf16 v[32:47], v[132:135], v[232:235], v[32:47]
	v_mfma_f32_32x32x16_bf16 v[16:31], v[224:227], v[232:235], v[16:31]
	v_mfma_f32_32x32x16_bf16 v[0:15], v[228:231], v[232:235], v[0:15]
	s_setprio 0
	s_andn2_b64 vcc, exec, s[66:67]
	s_cbranch_vccnz .LBB0_296

; #define MFMA32(a, b, c) __builtin_amdgcn_mfma_f32_32x32x16_bf16((a), (b), (c), 0, 0, 0)
; #define VFRAG(ptr, off0, STR) ({ const s16x4 lo_ = vtr((ptr) + (off0)); const s16x4 hi_ = vtr((ptr) + (off0) + 8 * (STR)); (bf16x8){lo_[0], lo_[1], lo_[2], lo_[3], hi_[0], hi_[1], hi_[2], hi_[3]}; })
; __device__ __forceinline__ void diff_unit(const Frame& F, int b, int h, int qi, float lam, int dry) {
;     ...
;             float ps = 0.f;
; #pragma unroll
;             for (int r = 0; r < 16; ++r) { s0[r] = __builtin_amdgcn_exp2f(s0[r] * LOG2E - ms); ps += s0[r]; }
;             if (!meta) {
; #pragma unroll
;                 for (int r = 0; r < 16; ++r) { s1[r] = __builtin_amdgcn_exp2f(s1[r] * LOG2E - ms); ps += s1[r]; }
;             }
;             lsum += ps;
;             __builtin_amdgcn_s_setprio(1);
;             { const bf16x8 pf = pack_step(s0, 0);
;               O[0] = MFMA32(vpre0, pf, O[0]); O[1] = MFMA32(vpre1, pf, O[1]); O[2] = MFMA32(vpre2, pf, O[2]); O[3] = MFMA32(vpre3, pf, O[3]); }
;             if (!meta) {
;                 { const bf16x8 pf = pack_step(s0, 1);
;                   O[0] = MFMA32(vprf0, pf, O[0]); O[1] = MFMA32(vprf1, pf, O[1]);
; #pragma unroll
;                   for (int dt = 2; dt < 4; ++dt) { const bf16x8 vf = VFRAG(vb, 16 * DV_STR + 64 * dt, DV_STR); O[dt] = MFMA32(vf, pf, O[dt]); } }
; #pragma unroll
;                 for (int s2 = 0; s2 < 2; ++s2) { const bf16x8 pf = pack_step(s1, s2);
; #pragma unroll
;                     for (int dt = 0; dt < 4; ++dt) { const bf16x8 vf = VFRAG(vb, (32 + 16 * s2) * DV_STR + 64 * dt, DV_STR); O[dt] = MFMA32(vf, pf, O[dt]); } }
;             }
;             __builtin_amdgcn_s_setprio(0);
.LBB0_324:
	s_setprio 1
	v_exp_f32_e32 v80, v80
	v_exp_f32_e32 v81, v81
	v_exp_f32_e32 v82, v82
	v_exp_f32_e32 v83, v83
	v_exp_f32_e32 v84, v84
	v_exp_f32_e32 v85, v85
	v_exp_f32_e32 v86, v86
	v_exp_f32_e32 v87, v87
	v_add_f32_e32 v202, v80, v82
	v_add_f32_e32 v203, v81, v83
	v_cvt_pk_bf16_f32 v198, v80, v81
	v_cvt_pk_bf16_f32 v199, v82, v83
	v_cvt_pk_bf16_f32 v200, v84, v85
	v_cvt_pk_bf16_f32 v201, v86, v87
	v_add_f32_e32 v202, v202, v84
	v_add_f32_e32 v203, v203, v85
	v_add_f32_e32 v202, v202, v86
	v_add_f32_e32 v203, v203, v87
	v_mfma_f32_32x32x16_bf16 v[48:63], v[148:151], v[198:201], v[48:63]
	ds_read_b64_tr_b16 v[148:149], v188 offset:45056
	ds_read_b64_tr_b16 v[150:151], v188 offset:47616
	v_exp_f32_e32 v88, v88
	v_exp_f32_e32 v89, v89
	v_mfma_f32_32x32x16_bf16 v[32:47], v[144:147], v[198:201], v[32:47]
	ds_read_b64_tr_b16 v[144:145], v188 offset:45120
	ds_read_b64_tr_b16 v[146:147], v188 offset:47680
	v_exp_f32_e32 v90, v90
	v_exp_f32_e32 v91, v91
	v_add_f32_e32 v202, v202, v88
	v_add_f32_e32 v203, v203, v89
	v_cvt_pk_bf16_f32 v80, v88, v89
	v_mfma_f32_32x32x16_bf16 v[16:31], v[140:143], v[198:201], v[16:31]
	ds_read_b64_tr_b16 v[140:141], v188 offset:45184
	ds_read_b64_tr_b16 v[142:143], v188 offset:47744
	v_exp_f32_e32 v92, v92
	v_exp_f32_e32 v93, v93
	v_add_f32_e32 v202, v202, v90
	v_add_f32_e32 v203, v203, v91
	v_cvt_pk_bf16_f32 v81, v90, v91
	v_mfma_f32_32x32x16_bf16 v[0:15], v[136:139], v[198:201], v[0:15]
	ds_read_b64_tr_b16 v[136:137], v188 offset:45248
	ds_read_b64_tr_b16 v[138:139], v188 offset:47808
	v_exp_f32_e32 v94, v94
	v_exp_f32_e32 v95, v95
	v_add_f32_e32 v202, v202, v92
	v_add_f32_e32 v203, v203, v93
	v_cvt_pk_bf16_f32 v82, v92, v93
	v_cvt_pk_bf16_f32 v83, v94, v95
	v_add_f32_e32 v202, v202, v94
	v_add_f32_e32 v203, v203, v95
	v_mfma_f32_32x32x16_bf16 v[48:63], v[128:131], v[80:83], v[48:63]
	ds_read_b64_tr_b16 v[128:129], v188 offset:50176
	ds_read_b64_tr_b16 v[130:131], v188 offset:52736
	v_exp_f32_e32 v64, v64
	v_exp_f32_e32 v65, v65
	v_mfma_f32_32x32x16_bf16 v[32:47], v[132:135], v[80:83], v[32:47]
	ds_read_b64_tr_b16 v[132:133], v188 offset:50240
	ds_read_b64_tr_b16 v[134:135], v188 offset:52800
	v_exp_f32_e32 v66, v66
	v_exp_f32_e32 v67, v67
	v_add_f32_e32 v202, v202, v64
	v_add_f32_e32 v203, v203, v65
	v_cvt_pk_bf16_f32 v84, v64, v65
	s_waitcnt lgkmcnt(14)
	v_mfma_f32_32x32x16_bf16 v[16:31], v[190:193], v[80:83], v[16:31]
	ds_read_b64_tr_b16 v[190:191], v188 offset:50304
	ds_read_b64_tr_b16 v[192:193], v188 offset:52864
	v_exp_f32_e32 v68, v68
	v_exp_f32_e32 v69, v69
	v_add_f32_e32 v202, v202, v66
	v_add_f32_e32 v203, v203, v67
	v_cvt_pk_bf16_f32 v85, v66, v67
	s_waitcnt lgkmcnt(14)
	v_mfma_f32_32x32x16_bf16 v[0:15], v[194:197], v[80:83], v[0:15]
	ds_read_b64_tr_b16 v[194:195], v188 offset:50368
	ds_read_b64_tr_b16 v[196:197], v188 offset:52928
	v_exp_f32_e32 v70, v70
	v_exp_f32_e32 v71, v71
	v_add_f32_e32 v202, v202, v68
	v_add_f32_e32 v203, v203, v69
	v_cvt_pk_bf16_f32 v86, v68, v69
	v_cvt_pk_bf16_f32 v87, v70, v71
	v_add_f32_e32 v202, v202, v70
	v_add_f32_e32 v203, v203, v71
	s_waitcnt lgkmcnt(8)
	v_mfma_f32_32x32x16_bf16 v[48:63], v[148:151], v[84:87], v[48:63]
	v_exp_f32_e32 v72, v72
	v_exp_f32_e32 v73, v73
	v_mfma_f32_32x32x16_bf16 v[32:47], v[144:147], v[84:87], v[32:47]
	v_exp_f32_e32 v74, v74
	v_exp_f32_e32 v75, v75
	v_add_f32_e32 v202, v202, v72
	v_add_f32_e32 v203, v203, v73
	v_cvt_pk_bf16_f32 v198, v72, v73
	v_mfma_f32_32x32x16_bf16 v[16:31], v[140:143], v[84:87], v[16:31]
	v_exp_f32_e32 v76, v76
	v_exp_f32_e32 v77, v77
	v_add_f32_e32 v202, v202, v74
	v_add_f32_e32 v203, v203, v75
	v_cvt_pk_bf16_f32 v199, v74, v75
	v_mfma_f32_32x32x16_bf16 v[0:15], v[136:139], v[84:87], v[0:15]
	v_exp_f32_e32 v78, v78
	v_exp_f32_e32 v79, v79
	v_add_f32_e32 v202, v202, v76
	v_add_f32_e32 v203, v203, v77
	v_cvt_pk_bf16_f32 v200, v76, v77
	v_cvt_pk_bf16_f32 v201, v78, v79
	v_add_f32_e32 v202, v202, v78
	v_add_f32_e32 v203, v203, v79
	v_add_f32_e32 v189, v202, v203
	v_add_f32_e32 v153, v153, v189
	s_waitcnt lgkmcnt(0)
	v_mfma_f32_32x32x16_bf16 v[48:63], v[128:131], v[198:201], v[48:63]
	v_mfma_f32_32x32x16_bf16 v[32:47], v[132:135], v[198:201], v[32:47]
	v_mfma_f32_32x32x16_bf16 v[16:31], v[190:193], v[198:201], v[16:31]
	v_mfma_f32_32x32x16_bf16 v[0:15], v[194:197], v[198:201], v[0:15]
	s_setprio 0
	s_andn2_b64 vcc, exec, s[90:91]
	s_cbranch_vccnz .LBB0_315
